# prologue de-serialisation in the up GEMM as well: rstd table computed after the first eight LDS-DMA tile loads are in flight (on top of the proj version)
# baseline (speedup 1.0000x reference)
.LBB0_381:
	v_readlane_b32 s4, v254, 8
	v_readlane_b32 s5, v254, 9
	s_andn2_b64 vcc, exec, s[4:5]
	v_readfirstlane_b32 s28, v248
	s_cbranch_vccnz .LBB0_412
	v_lshlrev_b32_e32 v0, 4, v248
	s_waitcnt vmcnt(0)
	v_add_u32_e32 v2, 0x2000, v0
	s_waitcnt vmcnt(4)
	v_ashrrev_i32_e32 v3, 31, v2
	v_lshrrev_b32_e32 v3, 22, v3
	v_add_u32_e32 v3, v2, v3
	v_ashrrev_i32_e32 v10, 10, v3
	v_mul_i32_i24_e32 v3, 0x400, v10
	v_sub_u32_e32 v2, v2, v3
	v_lshrrev_b32_e32 v3, 4, v2
	v_bitop3_b32 v2, v3, v2, 32 bitop3:0x6c
	v_ashrrev_i32_e32 v3, 31, v2
	s_mul_i32 s5, s16, 0xb00000
	v_lshrrev_b32_e32 v3, 26, v3
	s_mul_hi_i32 s4, s16, 0xb00000
	s_add_u32 s5, s8, s5
	v_add_u32_e32 v3, v2, v3
	v_lshlrev_b32_e32 v5, 3, v10
	s_addc_u32 s4, s9, s4
	v_ashrrev_i32_e32 v4, 6, v3
	v_and_b32_e32 v5, -16, v5
	v_and_b32_e32 v3, 0xc0, v3
	s_add_u32 s17, s5, 0x1000000
	v_add_u32_e32 v5, v4, v5
	v_sub_u32_e32 v2, v2, v3
	s_addc_u32 s70, s4, 0
	v_lshlrev_b32_e32 v6, 1, v5
	v_lshlrev_b32_e32 v7, 3, v5
	v_lshlrev_b32_e32 v8, 5, v10
	v_ashrrev_i16_sdwa v2, v214, sext(v2) dst_sel:DWORD dst_unused:UNUSED_PAD src0_sel:DWORD src1_sel:BYTE_0
	v_and_b32_e32 v3, 3, v4
	s_mov_b32 s4, 0x1fffe0
	v_lshrrev_b32_e32 v4, 2, v5
	v_and_b32_e32 v11, 0x1fff80, v6
	v_and_b32_e32 v12, 0x78, v7
	v_bfe_u32 v13, v5, 4, 2
	v_and_b32_e32 v8, 32, v8
	v_bfe_i32 v14, v2, 0, 16
	v_and_or_b32 v3, v5, s4, v3
	v_and_b32_e32 v4, 4, v4
	v_and_b32_e32 v5, 24, v6
	v_or3_b32 v7, v11, v12, v13
	v_add_lshl_u32 v2, v8, v14, 1
	v_or3_b32 v3, v3, v4, v5
	v_lshl_add_u32 v222, v7, 11, v2
	v_lshl_add_u32 v224, v3, 11, v2
	v_bfe_i32 v2, v248, 27, 1
	v_lshrrev_b32_e32 v2, 22, v2
	v_add_u32_e32 v2, v0, v2
	v_and_b32_e32 v2, 0xfffffc00, v2
	v_sub_u32_e32 v0, v0, v2
	v_lshrrev_b32_e32 v2, 4, v0
	v_ashrrev_i32_e32 v4, 31, v248
	v_bitop3_b32 v0, v2, v0, 32 bitop3:0x6c
	v_lshrrev_b32_e32 v4, 26, v4
	v_ashrrev_i32_e32 v2, 31, v0
	v_add_u32_e32 v4, v248, v4
	v_lshrrev_b32_e32 v2, 26, v2
	v_ashrrev_i32_e32 v15, 6, v4
	v_add_u32_e32 v2, v0, v2
	v_lshlrev_b32_e32 v4, 3, v15
	v_ashrrev_i32_e32 v3, 6, v2
	v_and_b32_e32 v4, -16, v4
	v_and_b32_e32 v2, 0xc0, v2
	s_ashr_i32 s29, s28, 6
	v_add_u32_e32 v4, v3, v4
	v_sub_u32_e32 v0, v0, v2
	v_and_b32_e32 v2, 3, v3
	s_ashr_i32 s71, s28, 8
	s_lshl_b32 s74, s29, 10
	v_lshlrev_b32_e32 v5, 1, v4
	v_lshlrev_b32_e32 v6, 3, v4
	v_lshlrev_b32_e32 v7, 5, v15
	v_ashrrev_i16_sdwa v0, v214, sext(v0) dst_sel:DWORD dst_unused:UNUSED_PAD src0_sel:DWORD src1_sel:BYTE_0
	v_and_or_b32 v2, v4, s4, v2
	v_lshrrev_b32_e32 v3, 2, v4
	v_readlane_b32 s4, v254, 54
	v_and_b32_e32 v16, 0x1fff80, v5
	v_and_b32_e32 v17, 0x78, v6
	s_waitcnt vmcnt(3)
	v_bfe_u32 v18, v4, 4, 2
	v_and_b32_e32 v7, 32, v7
	v_bfe_i32 v19, v0, 0, 16
	v_and_b32_e32 v3, 4, v3
	v_and_b32_e32 v4, 24, v5
	v_readlane_b32 s5, v254, 55
	s_add_u32 s38, s17, s4
	v_or3_b32 v6, v16, v17, v18
	v_add_lshl_u32 v0, v7, v19, 1
	v_or3_b32 v2, v2, v3, v4
	s_addc_u32 s39, s70, s5
	s_add_i32 s75, s74, 0
	v_lshl_add_u32 v226, v6, 11, v0
	v_lshl_add_u32 v0, v2, 11, v0
	s_add_i32 m0, s75, 0x10000
	v_writelane_b32 v255, s30, 15
	global_load_lds_dwordx4 v0, s[38:39]
	s_add_i32 m0, s75, 0x12000
	s_add_u32 s4, s38, 0x40000
	global_load_lds_dwordx4 v224, s[38:39]
	s_addc_u32 s5, s39, 0
	s_add_i32 m0, s75, 0x14000
	v_mov_b32_e32 v225, v1
	global_load_lds_dwordx4 v0, s[4:5]
	s_add_i32 m0, s75, 0x16000
	v_mov_b32_e32 v227, v1
	global_load_lds_dwordx4 v224, s[4:5]
	v_readlane_b32 s4, v255, 4
	v_readlane_b32 s5, v255, 5
	s_add_u32 s42, s12, s4
	s_addc_u32 s43, s13, s5
	s_add_i32 s76, s75, 0x2000
	s_mov_b32 m0, s75
	s_add_u32 s4, s42, 0x2000
	global_load_lds_dwordx4 v226, s[42:43]
	s_mov_b32 m0, s76
	s_addc_u32 s5, s43, 0
	s_add_i32 s77, s75, 0x4000
	global_load_lds_dwordx4 v222, s[42:43]
	s_mov_b32 m0, s77
	s_add_i32 s78, s75, 0x6000
	global_load_lds_dwordx4 v226, s[4:5]
	s_mov_b32 m0, s78
	s_cmp_eq_u32 s71, 1
	global_load_lds_dwordx4 v222, s[4:5]
	s_load_dwordx2 s[26:27], s[0:1], 0x48
	s_load_dword s79, s[88:89], 0x0
	s_cselect_b64 s[24:25], -1, 0
	s_cmp_lg_u32 s71, 1
	v_mov_b32_e32 v223, v1
	s_cselect_b64 s[44:45], -1, 0
	s_waitcnt lgkmcnt(0)
	s_lshr_b32 s4, s28, 6
	v_and_b32_e32 v20, 63, v248
	v_lshlrev_b32_e32 v20, 4, v20
	s_add_i32 s5, s4, 0
	s_lshl_b32 s6, s5, 8
	s_add_i32 s6, s6, s2
	s_and_b32 s7, s6, 7
	s_mul_i32 s7, s7, 0x160
	s_lshr_b32 s20, s6, 3
	s_add_i32 s7, s7, s20
	s_lshr_b32 s20, s7, 3
	s_mul_i32 s20, s20, 0x1746
	s_lshr_b32 s20, s20, 16
	s_mul_i32 s21, s20, 0x58
	s_sub_i32 s21, s7, s21
	s_and_b32 s21, s21, 3
	s_lshl_b32 s20, s20, 2
	s_add_i32 s20, s20, s21
	s_lshl_b32 s20, s20, 10
	v_add_u32_e32 v21, s20, v20
	global_load_dwordx4 v[24:27], v21, s[14:15]
	v_add_u32_e32 v21, 0x20000, v21
	global_load_dwordx4 v[28:31], v21, s[14:15]
	v_add_u32_e32 v21, 0x20000, v21
	global_load_dwordx4 v[32:35], v21, s[14:15]
	v_add_u32_e32 v21, 0x20000, v21
	global_load_dwordx4 v[36:39], v21, s[14:15]
	v_add_u32_e32 v21, 0x20000, v21
	global_load_dwordx4 v[40:43], v21, s[14:15]
	v_add_u32_e32 v21, 0x20000, v21
	global_load_dwordx4 v[44:47], v21, s[14:15]
	v_add_u32_e32 v21, 0x20000, v21
	global_load_dwordx4 v[48:51], v21, s[14:15]
	v_add_u32_e32 v21, 0x20000, v21
	global_load_dwordx4 v[52:55], v21, s[14:15]
	v_add_u32_e32 v21, 0x20000, v21
	global_load_dwordx4 v[56:59], v21, s[14:15]
	v_add_u32_e32 v21, 0x20000, v21
	global_load_dwordx4 v[60:63], v21, s[14:15]
	v_add_u32_e32 v21, 0x20000, v21
	global_load_dwordx4 v[64:67], v21, s[14:15]
	v_add_u32_e32 v21, 0x20000, v21
	global_load_dwordx4 v[68:71], v21, s[14:15]
	v_add_u32_e32 v21, 0x20000, v21
	global_load_dwordx4 v[72:75], v21, s[14:15]
	v_add_u32_e32 v21, 0x20000, v21
	global_load_dwordx4 v[76:79], v21, s[14:15]
	v_add_u32_e32 v21, 0x20000, v21
	global_load_dwordx4 v[80:83], v21, s[14:15]
	v_add_u32_e32 v21, 0x20000, v21
	global_load_dwordx4 v[84:87], v21, s[14:15]
	s_cmp_gt_u32 s4, 2
	s_cbranch_scc1 .Lupt_one
	s_add_i32 s5, s4, 8
	s_lshl_b32 s6, s5, 8
	s_add_i32 s6, s6, s2
	s_and_b32 s7, s6, 7
	s_mul_i32 s7, s7, 0x160
	s_lshr_b32 s20, s6, 3
	s_add_i32 s7, s7, s20
	s_lshr_b32 s20, s7, 3
	s_mul_i32 s20, s20, 0x1746
	s_lshr_b32 s20, s20, 16
	s_mul_i32 s21, s20, 0x58
	s_sub_i32 s21, s7, s21
	s_and_b32 s21, s21, 3
	s_lshl_b32 s20, s20, 2
	s_add_i32 s20, s20, s21
	s_lshl_b32 s20, s20, 10
	v_add_u32_e32 v21, s20, v20
	global_load_dwordx4 v[88:91], v21, s[14:15]
	v_add_u32_e32 v21, 0x20000, v21
	global_load_dwordx4 v[92:95], v21, s[14:15]
	v_add_u32_e32 v21, 0x20000, v21
	global_load_dwordx4 v[96:99], v21, s[14:15]
	v_add_u32_e32 v21, 0x20000, v21
	global_load_dwordx4 v[100:103], v21, s[14:15]
	v_add_u32_e32 v21, 0x20000, v21
	global_load_dwordx4 v[104:107], v21, s[14:15]
	v_add_u32_e32 v21, 0x20000, v21
	global_load_dwordx4 v[108:111], v21, s[14:15]
	v_add_u32_e32 v21, 0x20000, v21
	global_load_dwordx4 v[112:115], v21, s[14:15]
	v_add_u32_e32 v21, 0x20000, v21
	global_load_dwordx4 v[116:119], v21, s[14:15]
	v_add_u32_e32 v21, 0x20000, v21
	global_load_dwordx4 v[120:123], v21, s[14:15]
	v_add_u32_e32 v21, 0x20000, v21
	global_load_dwordx4 v[124:127], v21, s[14:15]
	v_add_u32_e32 v21, 0x20000, v21
	global_load_dwordx4 v[128:131], v21, s[14:15]
	v_add_u32_e32 v21, 0x20000, v21
	global_load_dwordx4 v[132:135], v21, s[14:15]
	v_add_u32_e32 v21, 0x20000, v21
	global_load_dwordx4 v[136:139], v21, s[14:15]
	v_add_u32_e32 v21, 0x20000, v21
	global_load_dwordx4 v[140:143], v21, s[14:15]
	v_add_u32_e32 v21, 0x20000, v21
	global_load_dwordx4 v[144:147], v21, s[14:15]
	v_add_u32_e32 v21, 0x20000, v21
	global_load_dwordx4 v[148:151], v21, s[14:15]
	s_waitcnt vmcnt(0)
	v_pk_add_f32 v[88:89], v[88:89], v[92:93]
	v_pk_add_f32 v[88:89], v[88:89], v[96:97]
	v_pk_add_f32 v[88:89], v[88:89], v[100:101]
	v_pk_add_f32 v[104:105], v[104:105], v[108:109]
	v_pk_add_f32 v[104:105], v[104:105], v[112:113]
	v_pk_add_f32 v[104:105], v[104:105], v[116:117]
	v_pk_add_f32 v[120:121], v[120:121], v[124:125]
	v_pk_add_f32 v[120:121], v[120:121], v[128:129]
	v_pk_add_f32 v[120:121], v[120:121], v[132:133]
	v_pk_add_f32 v[136:137], v[136:137], v[140:141]
	v_pk_add_f32 v[136:137], v[136:137], v[144:145]
	v_pk_add_f32 v[136:137], v[136:137], v[148:149]
	v_pk_add_f32 v[90:91], v[90:91], v[94:95]
	v_pk_add_f32 v[90:91], v[90:91], v[98:99]
	v_pk_add_f32 v[90:91], v[90:91], v[102:103]
	v_pk_add_f32 v[106:107], v[106:107], v[110:111]
	v_pk_add_f32 v[106:107], v[106:107], v[114:115]
	v_pk_add_f32 v[106:107], v[106:107], v[118:119]
	v_pk_add_f32 v[122:123], v[122:123], v[126:127]
	v_pk_add_f32 v[122:123], v[122:123], v[130:131]
	v_pk_add_f32 v[122:123], v[122:123], v[134:135]
	v_pk_add_f32 v[138:139], v[138:139], v[142:143]
	v_pk_add_f32 v[138:139], v[138:139], v[146:147]
	v_pk_add_f32 v[138:139], v[138:139], v[150:151]
	v_pk_add_f32 v[88:89], v[88:89], v[104:105]
	v_pk_add_f32 v[120:121], v[120:121], v[136:137]
	v_pk_add_f32 v[88:89], v[88:89], v[120:121]
	v_pk_add_f32 v[90:91], v[90:91], v[106:107]
	v_pk_add_f32 v[122:123], v[122:123], v[138:139]
	v_pk_add_f32 v[90:91], v[90:91], v[122:123]
	v_fma_f32 v88, v88, s90, v212
	v_fma_f32 v89, v89, s90, v212
	v_fma_f32 v90, v90, s90, v212
	v_fma_f32 v91, v91, s90, v212
	v_rsq_f32_e32 v88, v88
	v_rsq_f32_e32 v89, v89
	v_rsq_f32_e32 v90, v90
	v_rsq_f32_e32 v91, v91
	s_add_i32 s5, s4, 8
	s_lshl_b32 s5, s5, 10
	s_add_i32 s5, s5, 0x21000
	v_add_u32_e32 v21, s5, v20
	s_nop 0
	ds_write_b128 v21, v[88:91]
.Lupt_one:
	s_waitcnt vmcnt(0)
	v_pk_add_f32 v[24:25], v[24:25], v[28:29]
	v_pk_add_f32 v[24:25], v[24:25], v[32:33]
	v_pk_add_f32 v[24:25], v[24:25], v[36:37]
	v_pk_add_f32 v[40:41], v[40:41], v[44:45]
	v_pk_add_f32 v[40:41], v[40:41], v[48:49]
	v_pk_add_f32 v[40:41], v[40:41], v[52:53]
	v_pk_add_f32 v[56:57], v[56:57], v[60:61]
	v_pk_add_f32 v[56:57], v[56:57], v[64:65]
	v_pk_add_f32 v[56:57], v[56:57], v[68:69]
	v_pk_add_f32 v[72:73], v[72:73], v[76:77]
	v_pk_add_f32 v[72:73], v[72:73], v[80:81]
	v_pk_add_f32 v[72:73], v[72:73], v[84:85]
	v_pk_add_f32 v[26:27], v[26:27], v[30:31]
	v_pk_add_f32 v[26:27], v[26:27], v[34:35]
	v_pk_add_f32 v[26:27], v[26:27], v[38:39]
	v_pk_add_f32 v[42:43], v[42:43], v[46:47]
	v_pk_add_f32 v[42:43], v[42:43], v[50:51]
	v_pk_add_f32 v[42:43], v[42:43], v[54:55]
	v_pk_add_f32 v[58:59], v[58:59], v[62:63]
	v_pk_add_f32 v[58:59], v[58:59], v[66:67]
	v_pk_add_f32 v[58:59], v[58:59], v[70:71]
	v_pk_add_f32 v[74:75], v[74:75], v[78:79]
	v_pk_add_f32 v[74:75], v[74:75], v[82:83]
	v_pk_add_f32 v[74:75], v[74:75], v[86:87]
	v_pk_add_f32 v[24:25], v[24:25], v[40:41]
	v_pk_add_f32 v[56:57], v[56:57], v[72:73]
	v_pk_add_f32 v[24:25], v[24:25], v[56:57]
	v_pk_add_f32 v[26:27], v[26:27], v[42:43]
	v_pk_add_f32 v[58:59], v[58:59], v[74:75]
	v_pk_add_f32 v[26:27], v[26:27], v[58:59]
	v_fma_f32 v24, v24, s90, v212
	v_fma_f32 v25, v25, s90, v212
	v_fma_f32 v26, v26, s90, v212
	v_fma_f32 v27, v27, s90, v212
	v_rsq_f32_e32 v24, v24
	v_rsq_f32_e32 v25, v25
	v_rsq_f32_e32 v26, v26
	v_rsq_f32_e32 v27, v27
	s_add_i32 s5, s4, 0
	s_lshl_b32 s5, s5, 10
	s_add_i32 s5, s5, 0x21000
	v_add_u32_e32 v21, s5, v20
	s_nop 0
	ds_write_b128 v21, v[24:27]
	s_waitcnt lgkmcnt(0)
	v_lshl_add_u64 v[8:9], s[38:39], 0, v[0:1]
	v_lshl_add_u64 v[6:7], s[38:39], 0, v[224:225]
	v_lshl_add_u64 v[4:5], s[42:43], 0, v[226:227]
	v_lshl_add_u64 v[2:3], s[42:43], 0, v[222:223]
	s_and_b64 vcc, exec, s[44:45]
	s_cbranch_vccnz .LBB0_384
	s_barrier
